# FOX attention loop LDS reads batched into free VGPRs with counted lgkmcnt + per-XCD work queues for attention units (L2 locality)
# speedup vs baseline: 1.0078x; 1.0078x over previous
.LBB0_833:
	s_or_b64 exec, exec, s[4:5]
	s_waitcnt lgkmcnt(0)
	s_barrier
	v_mbcnt_lo_u32_b32 v6, -1, 0
	v_mbcnt_hi_u32_b32 v6, -1, v6
	s_getreg_b32 s2, hwreg(HW_REG_HW_ID, 0, 6)
	s_lshl_b32 s2, s2, 2
	s_and_b32 s2, s2, 0xfc
	s_add_i32 s2, s2, 0
	s_add_i32 s2, s2, 0x23400
	v_mov_b32_e32 v0, s2
	ds_read_b32 v7, v0
	s_load_dwordx16 s[16:31], s[84:85], 0x68
	s_load_dwordx4 s[40:43], s[84:85], 0xa8
	v_readlane_b32 s8, v255, 17
	s_load_dwordx2 s[4:5], s[84:85], 0x110
	v_readlane_b32 s6, v255, 31
	v_and_or_b32 v0, v6, 63, s8
	v_lshlrev_b64 v[2:3], 2, v[0:1]
	s_waitcnt lgkmcnt(0)
	v_lshl_add_u64 v[4:5], s[20:21], 0, v[2:3]
	global_load_dword v0, v[4:5], off
	v_lshl_add_u64 v[4:5], s[22:23], 0, v[2:3]
	global_load_dword v8, v[4:5], off
	v_lshl_add_u64 v[4:5], s[24:25], 0, v[2:3]
	global_load_dword v9, v[4:5], off
	v_lshl_add_u64 v[4:5], s[26:27], 0, v[2:3]
	global_load_dword v10, v[4:5], off
	v_lshl_add_u64 v[4:5], s[16:17], 0, v[2:3]
	global_load_dword v11, v[4:5], off
	v_lshl_add_u64 v[4:5], s[18:19], 0, v[2:3]
	global_load_dword v12, v[4:5], off
	v_lshl_add_u64 v[4:5], s[30:31], 0, v[2:3]
	global_load_dword v4, v[4:5], off
	v_lshl_add_u64 v[2:3], s[40:41], 0, v[2:3]
	global_load_dword v2, v[2:3], off
	v_readfirstlane_b32 s2, v7
	s_lshl_b32 s2, s2, 6
	s_add_u32 s94, s4, 0x11d00000
	s_addc_u32 s95, s5, 0
	s_add_u32 s96, s4, 0x15d00000
	s_addc_u32 s97, s5, 0
	s_add_u32 s56, s4, 0x19d00000
	s_addc_u32 s57, s5, 0
	s_add_u32 s77, s4, 0x600000
	s_addc_u32 s52, s5, 0
	v_readlane_b32 s7, v255, 32
	s_add_u32 s58, s28, s6
	s_addc_u32 s59, s29, s7
	v_readlane_b32 s6, v255, 19
	s_mov_b32 s3, s6
	s_mov_b32 s6, 0x3fb8aa3b
	s_cmp_eq_u32 s3, 0
	s_cselect_b64 vcc, -1, 0
	s_mov_b32 s3, 0x42b17218
	v_readlane_b32 s9, v255, 18
	v_readlane_b32 s7, v255, 20
	s_mov_b32 s65, s72
	s_waitcnt vmcnt(6)
	v_mul_f32_e32 v3, v0, v8
	ds_swizzle_b32 v3, v3 offset:swizzle(SWAP,1)
	s_waitcnt vmcnt(4)
	v_mul_f32_e32 v5, v9, v10
	ds_swizzle_b32 v5, v5 offset:swizzle(SWAP,1)
	s_waitcnt vmcnt(3)
	v_and_b32_e32 v7, 0x7fffffff, v11
	ds_swizzle_b32 v7, v7 offset:swizzle(SWAP,1)
	v_max_f32_e64 v11, |v11|, |v11|
	s_waitcnt lgkmcnt(2)
	v_fmac_f32_e32 v3, v0, v8
	s_waitcnt vmcnt(1)
	v_and_b32_e32 v14, 0x7fffffff, v4
	ds_swizzle_b32 v14, v14 offset:swizzle(SWAP,1)
	s_waitcnt lgkmcnt(1)
	v_max_f32_e32 v0, v7, v7
	v_max_f32_e64 v4, |v4|, |v4|
	v_max_f32_e32 v0, v11, v0
	v_fmac_f32_e32 v5, v9, v10
	s_waitcnt lgkmcnt(0)
	v_max_f32_e32 v8, v14, v14
	v_max_f32_e32 v4, v4, v8
	ds_swizzle_b32 v8, v0 offset:swizzle(SWAP,2)
	ds_swizzle_b32 v10, v3 offset:swizzle(SWAP,2)
	v_and_b32_e32 v13, 0x7fffffff, v12
	s_waitcnt vmcnt(0)
	v_and_b32_e32 v15, 0x7fffffff, v2
	ds_swizzle_b32 v13, v13 offset:swizzle(SWAP,1)
	s_waitcnt lgkmcnt(2)
	v_max_f32_e32 v8, v8, v8
	v_max_f32_e32 v0, v0, v8
	ds_swizzle_b32 v8, v0 offset:swizzle(SWAP,4)
	ds_swizzle_b32 v15, v15 offset:swizzle(SWAP,1)
	s_waitcnt lgkmcnt(3)
	v_add_f32_e32 v3, v3, v10
	ds_swizzle_b32 v10, v3 offset:swizzle(SWAP,4)
	v_max_f32_e64 v12, |v12|, |v12|
	s_waitcnt lgkmcnt(2)
	v_max_f32_e32 v8, v8, v8
	v_max_f32_e32 v0, v0, v8
	ds_swizzle_b32 v8, v0 offset:swizzle(SWAP,8)
	v_max_f32_e32 v7, v13, v13
	v_max_f32_e64 v2, |v2|, |v2|
	s_waitcnt lgkmcnt(2)
	v_max_f32_e32 v9, v15, v15
	v_max_f32_e32 v7, v12, v7
	s_waitcnt lgkmcnt(0)
	v_max_f32_e32 v8, v8, v8
	v_max_f32_e32 v0, v0, v8
	ds_swizzle_b32 v8, v0 offset:swizzle(SWAP,16)
	v_max_f32_e32 v2, v2, v9
	ds_swizzle_b32 v9, v7 offset:swizzle(SWAP,2)
	v_add_f32_e32 v3, v3, v10
	ds_swizzle_b32 v10, v3 offset:swizzle(SWAP,8)
	s_waitcnt lgkmcnt(2)
	v_max_f32_e32 v8, v8, v8
	v_max_f32_e32 v0, v0, v8
	v_mov_b32_e32 v8, v0
	s_nop 1
	v_permlane32_swap_b32_e32 v0, v8
	ds_swizzle_b32 v11, v4 offset:swizzle(SWAP,2)
	s_waitcnt lgkmcnt(2)
	v_max_f32_e32 v9, v9, v9
	v_max_f32_e32 v8, v8, v8
	v_max_f32_e32 v0, v0, v0
	v_max_f32_e32 v7, v7, v9
	v_max_f32_e32 v0, v0, v8
	ds_swizzle_b32 v8, v2 offset:swizzle(SWAP,2)
	ds_swizzle_b32 v9, v7 offset:swizzle(SWAP,4)
	s_waitcnt lgkmcnt(3)
	v_add_f32_e32 v3, v3, v10
	ds_swizzle_b32 v10, v3 offset:swizzle(SWAP,16)
	s_waitcnt lgkmcnt(3)
	v_max_f32_e32 v11, v11, v11
	v_max_f32_e32 v4, v4, v11
	s_waitcnt lgkmcnt(2)
	v_max_f32_e32 v8, v8, v8
	ds_swizzle_b32 v11, v4 offset:swizzle(SWAP,4)
	s_waitcnt lgkmcnt(2)
	v_max_f32_e32 v9, v9, v9
	v_max_f32_e32 v2, v2, v8
	v_max_f32_e32 v7, v7, v9
	ds_swizzle_b32 v8, v2 offset:swizzle(SWAP,4)
	ds_swizzle_b32 v9, v7 offset:swizzle(SWAP,8)
	s_waitcnt lgkmcnt(3)
	v_add_f32_e32 v3, v3, v10
	v_mov_b32_e32 v10, v3
	s_nop 1
	v_permlane32_swap_b32_e32 v3, v10
	v_add_f32_e32 v3, v3, v10
	s_waitcnt lgkmcnt(2)
	v_max_f32_e32 v10, v11, v11
	v_max_f32_e32 v4, v4, v10
	s_waitcnt lgkmcnt(1)
	v_max_f32_e32 v8, v8, v8
	s_waitcnt lgkmcnt(0)
	v_max_f32_e32 v9, v9, v9
	ds_swizzle_b32 v10, v4 offset:swizzle(SWAP,8)
	v_max_f32_e32 v2, v2, v8
	ds_swizzle_b32 v13, v5 offset:swizzle(SWAP,2)
	v_max_f32_e32 v7, v7, v9
	ds_swizzle_b32 v8, v2 offset:swizzle(SWAP,8)
	ds_swizzle_b32 v9, v7 offset:swizzle(SWAP,16)
	s_waitcnt lgkmcnt(3)
	v_max_f32_e32 v10, v10, v10
	s_waitcnt lgkmcnt(2)
	v_add_f32_e32 v5, v5, v13
	v_max_f32_e32 v4, v4, v10
	s_waitcnt lgkmcnt(1)
	v_max_f32_e32 v8, v8, v8
	ds_swizzle_b32 v12, v5 offset:swizzle(SWAP,4)
	s_waitcnt lgkmcnt(1)
	v_max_f32_e32 v9, v9, v9
	ds_swizzle_b32 v10, v4 offset:swizzle(SWAP,16)
	v_max_f32_e32 v2, v2, v8
	v_max_f32_e32 v7, v7, v9
	ds_swizzle_b32 v8, v2 offset:swizzle(SWAP,16)
	v_mov_b32_e32 v9, v7
	s_nop 1
	v_permlane32_swap_b32_e32 v7, v9
	v_max_f32_e32 v9, v9, v9
	v_max_f32_e32 v7, v7, v7
	s_waitcnt lgkmcnt(2)
	v_add_f32_e32 v5, v5, v12
	v_max_f32_e32 v7, v7, v9
	s_waitcnt lgkmcnt(1)
	v_max_f32_e32 v9, v10, v10
	ds_swizzle_b32 v12, v5 offset:swizzle(SWAP,8)
	v_max_f32_e32 v4, v4, v9
	s_waitcnt lgkmcnt(1)
	v_max_f32_e32 v8, v8, v8
	v_mov_b32_e32 v9, v4
	v_max_f32_e32 v2, v2, v8
	s_nop 0
	v_permlane32_swap_b32_e32 v4, v9
	v_mov_b32_e32 v8, v2
	v_max_f32_e32 v9, v9, v9
	v_max_f32_e32 v4, v4, v4
	v_permlane32_swap_b32_e32 v2, v8
	v_mul_f32_e32 v0, 0x413c5bb7, v0
	v_max_f32_e32 v4, v4, v9
	v_max_f32_e32 v8, v8, v8
	v_max_f32_e32 v2, v2, v2
	v_mul_f32_e32 v0, v0, v7
	s_waitcnt lgkmcnt(0)
	v_add_f32_e32 v5, v5, v12
	v_max_f32_e32 v2, v2, v8
	v_readfirstlane_b32 s80, v0
	v_mul_f32_e32 v0, 0x413c5bb7, v4
	ds_swizzle_b32 v12, v5 offset:swizzle(SWAP,16)
	v_mul_f32_e32 v0, v0, v2
	v_mov_b32_e32 v7, 0x3e4ccccd
	v_readfirstlane_b32 s81, v0
	v_mul_f32_e32 v0, 0x3fb8aa3b, v3
	v_fma_f32 v2, v3, s6, -v0
	v_rndne_f32_e32 v4, v0
	v_fmac_f32_e32 v2, 0x32a5705f, v3
	v_sub_f32_e32 v0, v0, v4
	v_add_f32_e32 v0, v0, v2
	s_waitcnt lgkmcnt(0)
	v_add_f32_e32 v5, v5, v12
	v_exp_f32_e32 v0, v0
	v_cvt_i32_f32_e32 v2, v4
	v_mov_b32_e32 v12, v5
	s_nop 1
	v_permlane32_swap_b32_e32 v5, v12
	v_add_f32_e32 v5, v5, v12
	v_mov_b32_e32 v4, 0x3ef1014c
	v_ldexp_f32 v0, v0, v2
	v_mul_f32_e32 v2, 0x3fb8aa3b, v5
	v_cndmask_b32_e32 v4, v4, v7, vcc
	v_fma_f32 v7, v5, s6, -v2
	v_rndne_f32_e32 v8, v2
	v_fmac_f32_e32 v7, 0x32a5705f, v5
	v_sub_f32_e32 v2, v2, v8
	v_add_f32_e32 v2, v2, v7
	v_exp_f32_e32 v2, v2
	v_cvt_i32_f32_e32 v7, v8
	v_cmp_ngt_f32_e32 vcc, s82, v3
	s_lshl_b64 s[6:7], s[8:9], 2
	v_sub_f32_e32 v134, 1.0, v4
	v_cndmask_b32_e32 v0, 0, v0, vcc
	v_cmp_nlt_f32_e32 vcc, s3, v3
	v_ldexp_f32 v2, v2, v7
	s_nop 0
	v_cndmask_b32_e32 v0, v229, v0, vcc
	v_cmp_ngt_f32_e32 vcc, s82, v5
	s_add_u32 s82, s4, s6
	s_addc_u32 s83, s5, s7
	v_cndmask_b32_e32 v2, 0, v2, vcc
	v_cmp_nlt_f32_e32 vcc, s3, v5
	s_nop 1
	v_cndmask_b32_e32 v2, v229, v2, vcc
	v_sub_f32_e32 v0, v0, v2
	v_add_f32_e32 v0, v0, v4
	s_nop 0
	v_readfirstlane_b32 s12, v0
	v_sub_u32_e32 v0, 0, v6
	v_cmp_eq_u32_e64 s[4:5], s2, v0
	s_mov_b32 s13, s12
	s_mov_b32 s100, 0
	s_branch .LBB0_837

.Lq_try:
	s_getreg_b32 s2, hwreg(HW_REG_XCC_ID, 0, 4)
	s_add_i32 s2, s2, s100
	s_and_b32 s2, s2, 7
	s_lshl_b32 s3, s2, 9
	s_add_i32 s3, s3, 0x300
	v_mov_b32_e32 v3, s3
	v_mov_b32_e32 v2, 1
	global_atomic_add v2, v3, v2, s[82:83] offset:256 sc0
	s_waitcnt vmcnt(0)
	v_readfirstlane_b32 s3, v2
	s_nop 0
	s_cmp_lt_u32 s3, 0x100
	s_cbranch_scc1 .Lq_got
	s_add_i32 s100, s100, 1
	s_cmp_lt_u32 s100, 8
	s_cbranch_scc1 .Lq_try
	s_movk_i32 s3, 0x7fff
	s_mov_b32 s2, 0
.Lq_got:
	s_lshl_b32 s2, s2, 8
	s_or_b32 s2, s2, s3
	v_mov_b32_e32 v0, s2
	v_mov_b32_e32 v2, s49
	ds_write_b32 v2, v0
.Lq_pub_done:
	s_or_b64 exec, exec, s[6:7]
	v_mov_b32_e32 v0, s49
	s_waitcnt lgkmcnt(0)
	s_barrier
	ds_read_b32 v0, v0
	s_waitcnt lgkmcnt(0)
	s_barrier
	v_readfirstlane_b32 s2, v0
	s_nop 0
	s_cmpk_gt_i32 s2, 0x7ff
	s_cbranch_scc1 .LBB0_886
	s_lshr_b32 s3, s2, 8
	s_and_b32 s2, s2, 0xff
	s_cmp_lt_u32 s2, 64
	s_cbranch_scc0 .Lq_mixed
	s_lshr_b32 s6, s2, 2
	s_sub_i32 s45, 32, s6
	s_and_b32 s6, s2, 3
	s_lshl_b32 s6, s6, 3
	s_add_i32 s78, s3, s6
	s_branch .LBB0_845
.Lq_mixed:
	s_sub_i32 s2, s2, 64
	s_mul_i32 s6, s2, 0xaaab
	s_lshr_b32 s6, s6, 19
	s_sub_i32 s45, 16, s6
	s_mul_i32 s6, s6, 12
	s_sub_i32 s2, s2, s6
	s_cmp_lt_u32 s2, 4
	s_cbranch_scc0 .Lq_fox
	s_lshl_b32 s6, s2, 3
	s_add_i32 s78, s3, s6
	s_branch .LBB0_845
.Lq_fox:
	s_sub_i32 s2, s2, 4
	s_lshl_b32 s6, s2, 3
	s_add_i32 s78, s3, s6
	s_branch .LBB0_872

.LBB0_861:
	s_mov_b32 s6, s3
	s_branch .LBB0_852
.LBB0_865:
	s_lshl_b32 s2, s91, 7
	s_waitcnt lgkmcnt(0)
	s_add_i32 s2, s2, 0
	v_mov_b32_e32 v0, v135
	s_add_i32 s2, s2, 0x10400
	s_nop 0
	v_permlane32_swap_b32_e32 v135, v0
	s_and_saveexec_b64 s[6:7], vcc
	s_cbranch_execz .LBB0_867
	v_add_f32_e32 v0, v135, v0
	v_rcp_f32_e32 v0, v0
	v_lshl_add_u32 v66, v130, 2, s2
	ds_write_b32 v66, v0

.LBB0_878:
	s_cmp_gt_i32 s6, s53
	s_cbranch_scc1 .LBB0_883
	v_lshl_add_u32 v252, s72, 8, v139
	s_lshl_b32 s6, s72, 15
	s_add_i32 s45, s6, 0
	ds_read_b128 v[80:83], v252
	ds_read_b128 v[84:87], v252 offset:32
	ds_read_b128 v[88:91], v252 offset:64
	ds_read_b128 v[92:95], v252 offset:96
	v_add3_u32 v253, s45, v140, v141
	ds_read_b128 v[96:99], v252 offset:128
	ds_read_b128 v[100:103], v252 offset:160
	ds_read_b128 v[104:107], v252 offset:192
	ds_read_b128 v[108:111], v252 offset:224
	v_add_u32_e32 v250, s45, v142
	ds_read_b128 v[146:149], v253
	ds_read_b128 v[150:153], v253 offset:512
	ds_read_b128 v[154:157], v253 offset:2048
	ds_read_b128 v[158:161], v253 offset:2560
	v_add3_u32 v250, v250, v129, v143
	ds_read_b128 v[162:165], v253 offset:4096
	ds_read_b128 v[166:169], v253 offset:4608
	ds_read_b128 v[180:183], v253 offset:6144
	ds_read_b128 v[184:187], v253 offset:6656
	s_waitcnt lgkmcnt(8)
	v_sub_f32_e32 v80, v48, v80
	v_sub_f32_e32 v81, v48, v81
	v_sub_f32_e32 v82, v48, v82
	v_sub_f32_e32 v83, v48, v83
	v_sub_f32_e32 v84, v48, v84
	v_sub_f32_e32 v85, v48, v85
	v_sub_f32_e32 v86, v48, v86
	v_sub_f32_e32 v87, v48, v87
	v_sub_f32_e32 v88, v48, v88
	v_sub_f32_e32 v89, v48, v89
	v_sub_f32_e32 v90, v48, v90
	v_sub_f32_e32 v91, v48, v91
	v_sub_f32_e32 v92, v48, v92
	v_sub_f32_e32 v93, v48, v93
	v_sub_f32_e32 v94, v48, v94
	v_sub_f32_e32 v95, v48, v95
	ds_read_b64_tr_b16 v[188:189], v250 offset:16384
	ds_read_b64_tr_b16 v[190:191], v250 offset:16896
	ds_read_b64_tr_b16 v[192:193], v250 offset:17408
	ds_read_b64_tr_b16 v[194:195], v250 offset:17920
	v_sub_f32_e32 v96, v48, v96
	v_sub_f32_e32 v97, v48, v97
	v_sub_f32_e32 v98, v48, v98
	v_sub_f32_e32 v99, v48, v99
	v_sub_f32_e32 v100, v48, v100
	v_sub_f32_e32 v101, v48, v101
	v_sub_f32_e32 v102, v48, v102
	v_sub_f32_e32 v103, v48, v103
	v_sub_f32_e32 v104, v48, v104
	v_sub_f32_e32 v105, v48, v105
	v_sub_f32_e32 v106, v48, v106
	v_sub_f32_e32 v107, v48, v107
	v_sub_f32_e32 v108, v48, v108
	v_sub_f32_e32 v109, v48, v109
	v_sub_f32_e32 v110, v48, v110
	v_sub_f32_e32 v111, v48, v111
	ds_read_b64_tr_b16 v[196:197], v250 offset:18432
	ds_read_b64_tr_b16 v[198:199], v250 offset:18944
	ds_read_b64_tr_b16 v[200:201], v250 offset:19456
	s_waitcnt lgkmcnt(14)
	v_mfma_f32_32x32x16_bf16 v[80:95], v[146:149], v[112:115], v[80:95]
	s_waitcnt lgkmcnt(13)
	v_mfma_f32_32x32x16_bf16 v[96:111], v[150:153], v[112:115], v[96:111]
	ds_read_b64_tr_b16 v[202:203], v250 offset:19968
	s_waitcnt lgkmcnt(13)
	v_mfma_f32_32x32x16_bf16 v[80:95], v[154:157], v[116:119], v[80:95]
	s_waitcnt lgkmcnt(12)
	v_mfma_f32_32x32x16_bf16 v[96:111], v[158:161], v[116:119], v[96:111]
	ds_read_b64_tr_b16 v[204:205], v250 offset:20480
	ds_read_b64_tr_b16 v[206:207], v250 offset:20992
	s_waitcnt lgkmcnt(13)
	v_mfma_f32_32x32x16_bf16 v[80:95], v[162:165], v[120:123], v[80:95]
	s_waitcnt lgkmcnt(12)
	v_mfma_f32_32x32x16_bf16 v[96:111], v[166:169], v[120:123], v[96:111]
	ds_read_b64_tr_b16 v[208:209], v250 offset:21504
	ds_read_b64_tr_b16 v[210:211], v250 offset:22016
	s_waitcnt lgkmcnt(13)
	v_mfma_f32_32x32x16_bf16 v[80:95], v[180:183], v[124:127], v[80:95]
	s_waitcnt lgkmcnt(12)
	v_mfma_f32_32x32x16_bf16 v[96:111], v[184:187], v[124:127], v[96:111]
	ds_read_b64_tr_b16 v[212:213], v250 offset:22528
	ds_read_b64_tr_b16 v[214:215], v250 offset:23040
	ds_read_b64_tr_b16 v[216:217], v250 offset:23552
	ds_read_b64_tr_b16 v[218:219], v250 offset:24064
	s_mov_b32 s46, s44
	s_mov_b32 s47, s44
	s_mov_b32 s45, s44
	s_cmp_le_i32 s60, s40
	s_cbranch_scc1 .LBB0_881
	v_cmp_gt_i32_e32 vcc, 0, v144
	v_cmp_gt_i32_e64 s[6:7], 1, v144
	s_and_b64 vcc, s[6:7], vcc
	s_nop 4
	v_cndmask_b32_e32 v80, v80, v235, vcc
	v_cmp_lt_i32_e32 vcc, 1, v144
	v_cmp_gt_i32_e64 s[36:37], 58, v144
	v_cmp_gt_i32_e64 s[38:39], 59, v144
	v_cndmask_b32_e32 v82, v235, v82, vcc
	v_cmp_lt_i32_e32 vcc, 2, v144
	v_cmp_gt_i32_e64 s[34:35], 57, v144
	s_and_b64 s[36:37], s[38:39], s[36:37]
	v_cndmask_b32_e32 v83, v235, v83, vcc
	v_cmp_lt_i32_e32 vcc, 7, v144
	v_cmp_gt_i32_e64 s[30:31], 56, v144
	s_and_b64 s[34:35], s[36:37], s[34:35]
	v_cndmask_b32_e32 v84, v235, v84, vcc
	v_cmp_lt_i32_e32 vcc, 8, v144
	v_cmp_gt_i32_e64 s[28:29], 51, v144
	s_and_b64 s[30:31], s[34:35], s[30:31]
	v_cndmask_b32_e32 v85, v235, v85, vcc
	v_cmp_lt_i32_e32 vcc, 9, v144
	v_cmp_gt_i32_e64 s[26:27], 50, v144
	s_and_b64 s[28:29], s[30:31], s[28:29]
	v_cndmask_b32_e32 v86, v235, v86, vcc
	v_cmp_lt_i32_e32 vcc, 10, v144
	v_cmp_gt_i32_e64 s[24:25], 49, v144
	s_and_b64 s[26:27], s[28:29], s[26:27]
	v_cndmask_b32_e32 v87, v235, v87, vcc
	v_cmp_lt_i32_e32 vcc, 15, v144
	v_cmp_gt_i32_e64 s[22:23], 48, v144
	s_and_b64 s[24:25], s[26:27], s[24:25]
	v_cndmask_b32_e32 v88, v235, v88, vcc
	v_cmp_lt_i32_e32 vcc, 16, v144
	v_cmp_gt_i32_e64 s[20:21], 43, v144
	s_and_b64 s[22:23], s[24:25], s[22:23]
	v_cndmask_b32_e32 v89, v235, v89, vcc
	v_cmp_lt_i32_e32 vcc, 17, v144
	v_cmp_gt_i32_e64 s[18:19], 42, v144
	s_and_b64 s[20:21], s[22:23], s[20:21]
	v_cndmask_b32_e32 v90, v235, v90, vcc
	v_cmp_lt_i32_e32 vcc, 18, v144
	v_cmp_gt_i32_e64 s[16:17], 41, v144
	s_and_b64 s[18:19], s[20:21], s[18:19]
	v_cndmask_b32_e32 v91, v235, v91, vcc
	v_cmp_lt_i32_e32 vcc, 23, v144
	v_cmp_gt_i32_e64 s[14:15], 40, v144
	s_and_b64 s[16:17], s[18:19], s[16:17]
	v_cndmask_b32_e32 v92, v235, v92, vcc
	v_cmp_lt_i32_e32 vcc, 24, v144
	v_cmp_gt_i32_e64 s[10:11], 35, v144
	s_and_b64 s[14:15], s[16:17], s[14:15]
	v_cndmask_b32_e32 v93, v235, v93, vcc
	v_cmp_lt_i32_e32 vcc, 25, v144
	v_cmp_gt_i32_e64 s[8:9], 34, v144
	s_and_b64 s[10:11], s[14:15], s[10:11]
	v_cndmask_b32_e64 v81, v81, v235, s[6:7]
	v_cndmask_b32_e32 v94, v235, v94, vcc
	v_cmp_lt_i32_e32 vcc, 26, v144
	v_cmp_gt_i32_e64 s[6:7], 33, v144
	s_and_b64 s[8:9], s[10:11], s[8:9]
	v_cndmask_b32_e32 v0, v235, v95, vcc
	v_cmp_gt_i32_e32 vcc, 32, v144
	s_and_b64 s[6:7], s[8:9], s[6:7]
	s_and_b64 vcc, s[6:7], vcc
	v_cndmask_b32_e64 v111, v111, v235, s[38:39]
	v_cndmask_b32_e64 v110, v110, v235, s[36:37]
	v_cndmask_b32_e64 v109, v109, v235, s[34:35]
	v_cndmask_b32_e64 v108, v108, v235, s[30:31]
	v_cndmask_b32_e64 v107, v107, v235, s[28:29]
	v_cndmask_b32_e64 v106, v106, v235, s[26:27]
	v_cndmask_b32_e64 v105, v105, v235, s[24:25]
	v_cndmask_b32_e64 v104, v104, v235, s[22:23]
	v_cndmask_b32_e64 v103, v103, v235, s[20:21]
	v_cndmask_b32_e64 v102, v102, v235, s[18:19]
	v_cndmask_b32_e64 v101, v101, v235, s[16:17]
	v_cndmask_b32_e64 v100, v100, v235, s[14:15]
	v_cndmask_b32_e64 v99, v99, v235, s[10:11]
	v_cndmask_b32_e64 v98, v98, v235, s[8:9]
	v_cndmask_b32_e64 v97, v97, v235, s[6:7]
	v_cndmask_b32_e32 v95, v95, v0, vcc
	v_cndmask_b32_e32 v96, v96, v235, vcc
.LBB0_881:
	v_mov_b32_e32 v236, s44
	v_mov_b32_e32 v237, s44
	v_mov_b32_e32 v238, s44
	v_mov_b32_e32 v239, s44
	v_exp_f32_e32 v80, v80
	v_exp_f32_e32 v81, v81
	v_exp_f32_e32 v82, v82
	v_exp_f32_e32 v83, v83
	v_exp_f32_e32 v84, v84
	v_exp_f32_e32 v85, v85
	v_exp_f32_e32 v86, v86
	v_exp_f32_e32 v87, v87
	v_exp_f32_e32 v88, v88
	v_exp_f32_e32 v89, v89
	v_exp_f32_e32 v90, v90
	v_exp_f32_e32 v91, v91
	v_exp_f32_e32 v92, v92
	v_exp_f32_e32 v93, v93
	v_exp_f32_e32 v94, v94
	v_exp_f32_e32 v95, v95
	v_cvt_pk_bf16_f32 v2, v80, v81
	v_cvt_pk_bf16_f32 v3, v82, v83
	v_cvt_pk_bf16_f32 v4, v84, v85
	v_cvt_pk_bf16_f32 v5, v86, v87
	v_cvt_pk_bf16_f32 v6, v88, v89
	v_cvt_pk_bf16_f32 v7, v90, v91
	v_cvt_pk_bf16_f32 v8, v92, v93
	v_cvt_pk_bf16_f32 v9, v94, v95
	s_waitcnt lgkmcnt(0)
	v_mfma_f32_32x32x16_bf16 v[32:47], v[2:5], v[188:191], v[32:47]
	v_exp_f32_e32 v96, v96
	v_exp_f32_e32 v97, v97
	v_exp_f32_e32 v98, v98
	v_mfma_f32_32x32x16_bf16 v[32:47], v[6:9], v[192:195], v[32:47]
	v_exp_f32_e32 v99, v99
	v_exp_f32_e32 v100, v100
	v_exp_f32_e32 v101, v101
	v_mfma_f32_32x32x16_bf16 v[16:31], v[2:5], v[204:207], v[16:31]
	v_exp_f32_e32 v102, v102
	v_exp_f32_e32 v103, v103
	v_exp_f32_e32 v104, v104
	v_mfma_f32_32x32x16_bf16 v[16:31], v[6:9], v[208:211], v[16:31]
	v_exp_f32_e32 v105, v105
	v_exp_f32_e32 v106, v106
	v_exp_f32_e32 v107, v107
	v_mfma_f32_32x32x16_bf16 v[62:77], v[2:5], v[236:239], v[62:77]
	v_exp_f32_e32 v108, v108
	v_exp_f32_e32 v109, v109
	v_exp_f32_e32 v110, v110
	v_mfma_f32_32x32x16_bf16 v[62:77], v[6:9], v[236:239], v[62:77]
	v_exp_f32_e32 v111, v111
	v_cvt_pk_bf16_f32 v10, v96, v97
	v_cvt_pk_bf16_f32 v11, v98, v99
	v_cvt_pk_bf16_f32 v12, v100, v101
	v_cvt_pk_bf16_f32 v13, v102, v103
	v_cvt_pk_bf16_f32 v80, v104, v105
	v_cvt_pk_bf16_f32 v81, v106, v107
	v_cvt_pk_bf16_f32 v82, v108, v109
	v_cvt_pk_bf16_f32 v83, v110, v111
	v_mfma_f32_32x32x16_bf16 v[32:47], v[10:13], v[196:199], v[32:47]
	v_mfma_f32_32x32x16_bf16 v[16:31], v[10:13], v[212:215], v[16:31]
	v_mfma_f32_32x32x16_bf16 v[62:77], v[10:13], v[236:239], v[62:77]
	v_mfma_f32_32x32x16_bf16 v[32:47], v[80:83], v[200:203], v[32:47]
	v_mfma_f32_32x32x16_bf16 v[16:31], v[80:83], v[216:219], v[16:31]
	v_mfma_f32_32x32x16_bf16 v[62:77], v[80:83], v[236:239], v[62:77]
	s_or_b64 s[6:7], s[84:85], s[78:79]
	s_and_b64 vcc, exec, s[6:7]
	s_cbranch_vccz .LBB0_884

	.amdhsa_kernel _Z14fwd_megakernel4Args
		.amdhsa_group_segment_fixed_size 0
		.amdhsa_private_segment_fixed_size 0
		.amdhsa_kernarg_size 536
		.amdhsa_user_sgpr_count 2
		.amdhsa_user_sgpr_dispatch_ptr 0
		.amdhsa_user_sgpr_queue_ptr 0
		.amdhsa_user_sgpr_kernarg_segment_ptr 1
		.amdhsa_user_sgpr_dispatch_id 0
		.amdhsa_user_sgpr_kernarg_preload_length 0
		.amdhsa_user_sgpr_kernarg_preload_offset 0
		.amdhsa_user_sgpr_private_segment_size 0
		.amdhsa_uses_dynamic_stack 0
		.amdhsa_enable_private_segment 0
		.amdhsa_system_sgpr_workgroup_id_x 1
		.amdhsa_system_sgpr_workgroup_id_y 0
		.amdhsa_system_sgpr_workgroup_id_z 0
		.amdhsa_system_sgpr_workgroup_info 0
		.amdhsa_system_vgpr_workitem_id 2
		.amdhsa_next_free_vgpr 256
		.amdhsa_next_free_sgpr 102
		.amdhsa_accum_offset 256
		.amdhsa_reserve_vcc 1
		.amdhsa_float_round_mode_32 0
		.amdhsa_float_round_mode_16_64 0
		.amdhsa_float_denorm_mode_32 3
		.amdhsa_float_denorm_mode_16_64 3
		.amdhsa_dx10_clamp 1
		.amdhsa_ieee_mode 1
		.amdhsa_fp16_overflow 0
		.amdhsa_tg_split 0
		.amdhsa_exception_fp_ieee_invalid_op 0
		.amdhsa_exception_fp_denorm_src 0
		.amdhsa_exception_fp_ieee_div_zero 0
		.amdhsa_exception_fp_ieee_overflow 0
		.amdhsa_exception_fp_ieee_underflow 0
		.amdhsa_exception_fp_ieee_inexact 0
		.amdhsa_exception_int_div_zero 0
	.end_amdhsa_kernel

amdhsa.kernels:
  - .agpr_count:     0
    .args:
      - .offset:         0
        .size:           280
        .value_kind:     by_value
      - .offset:         280
        .size:           4
        .value_kind:     hidden_block_count_x
      - .offset:         284
        .size:           4
        .value_kind:     hidden_block_count_y
      - .offset:         288
        .size:           4
        .value_kind:     hidden_block_count_z
      - .offset:         292
        .size:           2
        .value_kind:     hidden_group_size_x
      - .offset:         294
        .size:           2
        .value_kind:     hidden_group_size_y
      - .offset:         296
        .size:           2
        .value_kind:     hidden_group_size_z
      - .offset:         298
        .size:           2
        .value_kind:     hidden_remainder_x
      - .offset:         300
        .size:           2
        .value_kind:     hidden_remainder_y
      - .offset:         302
        .size:           2
        .value_kind:     hidden_remainder_z
      - .offset:         320
        .size:           8
        .value_kind:     hidden_global_offset_x
      - .offset:         328
        .size:           8
        .value_kind:     hidden_global_offset_y
      - .offset:         336
        .size:           8
        .value_kind:     hidden_global_offset_z
      - .offset:         344
        .size:           2
        .value_kind:     hidden_grid_dims
      - .offset:         368
        .size:           8
        .value_kind:     hidden_multigrid_sync_arg
      - .offset:         400
        .size:           4
        .value_kind:     hidden_dynamic_lds_size
    .group_segment_fixed_size: 0
    .kernarg_segment_align: 8
    .kernarg_segment_size: 536
    .language:       OpenCL C
    .language_version:
      - 2
      - 0
    .max_flat_workgroup_size: 512
    .name:           _Z14fwd_megakernel4Args
    .private_segment_fixed_size: 0
    .sgpr_count:     108
    .sgpr_spill_count: 36
    .symbol:         _Z14fwd_megakernel4Args.kd
    .uniform_work_group_size: 1
    .uses_dynamic_stack: false
    .vgpr_count:     256
    .vgpr_spill_count: 0
    .wavefront_size: 64
